# grid barrier: replicated release counter (16 copies) + two staggered polls in flight per workgroup
# baseline (speedup 1.0000x reference)
.Lxb_wait_0:
	buffer_inv sc1
	v_readlane_b32 s16, v252, 5
	s_nop 3
	s_and_b32 s16, s16, 15
	s_lshl_b32 s16, s16, 8
	s_add_u32 s14, s14, s16
	s_addc_u32 s15, s15, 0
	s_mov_b32 s16, 0
	global_load_dword v254, v6, s[14:15] sc1
	s_sleep 8
